# Epi gemm phases: un-aligned epilogues (each half's epilogue overlaps the other half's MFMA segment)
# baseline (speedup 1.0000x reference)
; #define PG8_STAGE(bufoff, gbase, voff) do { _Pragma("unroll") for (int _i = 0; _i < 2; ++_i) \
;         __builtin_amdgcn_global_load_lds((const unsigned*)((const char*)(gbase) + (voff)[_i]), (PG8_LAS unsigned*)(lds + (bufoff) + ldsw + _i * 8192), 16, 0, 0); } while (0)
; #define PG8_LDA(dst, b, h) do { _Pragma("unroll") for (int m = 0; m < 4; ++m) _Pragma("unroll") for (int k = 0; k < 2; ++k) dst[m][k] = *(const PG8_LAS bf16x8*)(lds + PG8_SA(b, h) + aoff + m * 2048 + k * 1024); } while (0)
; #define PG8_LDB(dst, b, h) do { _Pragma("unroll") for (int n = 0; n < 2; ++n) _Pragma("unroll") for (int k = 0; k < 2; ++k) dst[n][k] = *(const PG8_LAS bf16x8*)(lds + PG8_SB(b, h) + boff + n * 2048 + k * 1024); } while (0)
; #define PG8_MMA(ai, bj, At, Bt) do { __builtin_amdgcn_s_setprio(1); _Pragma("unroll") for (int m = 0; m < 4; ++m) _Pragma("unroll") for (int n = 0; n < 2; ++n) _Pragma("unroll") for (int k = 0; k < 2; ++k) \
;         acc[ai][bj][m][n] = __builtin_amdgcn_mfma_f32_16x16x32_bf16(Bt[n][k], At[m][k], acc[ai][bj][m][n], 0, 0, 0); __builtin_amdgcn_s_setprio(0); } while (0)
; #define PG8_WAIT_V(n) asm volatile("s_waitcnt vmcnt(" #n ")" ::: "memory")
; #define PG8_WAIT_L(n) asm volatile("s_waitcnt lgkmcnt(" #n ")" ::: "memory")
; #define PG8_BAR __builtin_amdgcn_s_barrier()
; template <class Epi, class Sched, bool ALIGN_EPI = false, bool SP2 = false>
; __device__ __forceinline__ void gemm_phase(PG8_LAS unsigned char* lds, const Gemm g, const Sched& S, const Epi& E, const int wid_) {
;     ...
;         for (int t = 0; t < nt; t += 2) {
;             const bool last = (t == nt - 2);
;             const char* a1 = cA + (size_t)(t + 1) * kstep;
;             const char* a2 = last ? nA : cA + (size_t)(t + 2) * kstep; const char* b2 = last ? nB : cB + (size_t)(t + 2) * kstep;
;             const char* a3 = a2 + kstep; const char* b3 = b2 + kstep;
;             if (last && has_next) S.a_ready(nxt);
;             if constexpr (SP2) {
;             PG8_LDB(B0, 0, 0); PG8_LDB(B1, 0, 1); PG8_SCHED; PG8_LDA(At, 0, 0); PG8_STAGE(PG8_SA(1, 1), a1 + hstepA, voffA);
;             PG8_WAIT_V(8); PG8_WAIT_L(0); PG8_BAR; PG8_MMA(0, 0, At, B0); PG8_MMA(0, 1, At, B1); PG8_BAR; PG8_SCHED;
;             PG8_LDA(At, 0, 1); PG8_STAGE(PG8_SB(0, 0), b2, voffB); PG8_STAGE(PG8_SB(0, 1), b2 + hstepB, voffB); PG8_STAGE(PG8_SA(0, 0), a2, voffA);
.Lprio_a:
.LBB0_380:
	s_add_i32 s97, s38, 2
	s_add_u32 s98, s6, 0x80
	s_addc_u32 s39, s7, 0
	s_cmp_eq_u32 s41, s38
	s_cselect_b32 s39, s47, s39
	s_cselect_b32 s38, s46, s98
	s_cselect_b32 s99, s61, s62
	s_cselect_b32 s98, s60, s49
	s_add_i32 vcc_lo, 0, 0x14000
	v_add_u32_e32 v164, s42, v180
	v_add_u32_e32 v176, vcc_lo, v180
	ds_read_b128 v[128:131], v164
	ds_read_b128 v[132:135], v164 offset:1024
	ds_read_b128 v[136:139], v164 offset:2048
	ds_read_b128 v[164:167], v164 offset:3072
	ds_read_b128 v[168:171], v176
	ds_read_b128 v[172:175], v176 offset:1024
	ds_read_b128 v[182:185], v176 offset:2048
	ds_read_b128 v[186:189], v176 offset:3072
	v_lshl_add_u64 v[178:179], s[6:7], 0, v[162:163]
	s_add_i32 m0, s36, 0xc000
	ds_read_b128 v[190:193], v181
	ds_read_b128 v[194:197], v181 offset:1024
	ds_read_b128 v[198:201], v181 offset:2048
	ds_read_b128 v[202:205], v181 offset:3072
	ds_read_b128 v[206:209], v181 offset:4096
	ds_read_b128 v[212:215], v181 offset:5120
	ds_read_b128 v[216:219], v181 offset:6144
	ds_read_b128 v[220:223], v181 offset:7168
	global_load_lds_dwordx4 v[178:179], off
	v_lshl_add_u64 v[178:179], s[6:7], 0, v[160:161]
	s_add_i32 m0, s36, 0xe000
	s_nop 0
	global_load_lds_dwordx4 v[178:179], off
	s_waitcnt vmcnt(8)
	s_waitcnt lgkmcnt(0)
	s_barrier
	s_waitcnt lgkmcnt(0)
	v_mfma_f32_16x16x32_bf16 v[124:127], v[128:131], v[190:193], v[124:127]
	v_mfma_f32_16x16x32_bf16 v[120:123], v[136:139], v[190:193], v[120:123]
	v_mfma_f32_16x16x32_bf16 v[116:119], v[128:131], v[198:201], v[116:119]
	v_mfma_f32_16x16x32_bf16 v[112:115], v[136:139], v[198:201], v[112:115]
	v_mfma_f32_16x16x32_bf16 v[100:103], v[128:131], v[206:209], v[100:103]
	v_mfma_f32_16x16x32_bf16 v[96:99], v[136:139], v[206:209], v[96:99]
	v_mfma_f32_16x16x32_bf16 v[84:87], v[128:131], v[216:219], v[84:87]
	v_mfma_f32_16x16x32_bf16 v[80:83], v[136:139], v[216:219], v[80:83]
	v_mfma_f32_16x16x32_bf16 v[124:127], v[132:135], v[194:197], v[124:127]
	v_mfma_f32_16x16x32_bf16 v[120:123], v[164:167], v[194:197], v[120:123]
	v_mfma_f32_16x16x32_bf16 v[116:119], v[132:135], v[202:205], v[116:119]
	v_mfma_f32_16x16x32_bf16 v[112:115], v[164:167], v[202:205], v[112:115]
	v_mfma_f32_16x16x32_bf16 v[100:103], v[132:135], v[212:215], v[100:103]
	v_mfma_f32_16x16x32_bf16 v[96:99], v[164:167], v[212:215], v[96:99]
	v_mfma_f32_16x16x32_bf16 v[84:87], v[132:135], v[220:223], v[84:87]
	v_mfma_f32_16x16x32_bf16 v[80:83], v[164:167], v[220:223], v[80:83]
	v_mfma_f32_16x16x32_bf16 v[108:111], v[168:171], v[190:193], v[108:111]
	v_mfma_f32_16x16x32_bf16 v[104:107], v[182:185], v[190:193], v[104:107]
	v_mfma_f32_16x16x32_bf16 v[92:95], v[168:171], v[198:201], v[92:95]
	v_mfma_f32_16x16x32_bf16 v[88:91], v[182:185], v[198:201], v[88:91]
	v_mfma_f32_16x16x32_bf16 v[76:79], v[168:171], v[206:209], v[76:79]
	v_mfma_f32_16x16x32_bf16 v[72:75], v[182:185], v[206:209], v[72:75]
	v_mfma_f32_16x16x32_bf16 v[68:71], v[168:171], v[216:219], v[68:71]
	v_mfma_f32_16x16x32_bf16 v[64:67], v[182:185], v[216:219], v[64:67]
	v_mfma_f32_16x16x32_bf16 v[108:111], v[172:175], v[194:197], v[108:111]
	v_mfma_f32_16x16x32_bf16 v[104:107], v[186:189], v[194:197], v[104:107]
	v_mfma_f32_16x16x32_bf16 v[92:95], v[172:175], v[202:205], v[92:95]
	v_mfma_f32_16x16x32_bf16 v[88:91], v[186:189], v[202:205], v[88:91]
	v_mfma_f32_16x16x32_bf16 v[76:79], v[172:175], v[212:215], v[76:79]
	v_mfma_f32_16x16x32_bf16 v[72:75], v[186:189], v[212:215], v[72:75]
	v_mfma_f32_16x16x32_bf16 v[68:71], v[172:175], v[220:223], v[68:71]
	v_mfma_f32_16x16x32_bf16 v[64:67], v[186:189], v[220:223], v[64:67]
	s_barrier
	s_add_i32 vcc_hi, s42, s83
	v_lshl_add_u64 v[178:179], s[98:99], 0, v[142:143]
	s_mov_b32 m0, vcc_hi
	ds_read_b128 v[190:193], v181 offset:16384
	ds_read_b128 v[194:197], v181 offset:17408
	ds_read_b128 v[198:201], v181 offset:18432
	ds_read_b128 v[202:205], v181 offset:19456
	ds_read_b128 v[206:209], v181 offset:20480
	ds_read_b128 v[212:215], v181 offset:21504
	ds_read_b128 v[216:219], v181 offset:22528
	ds_read_b128 v[220:223], v181 offset:23552
	global_load_lds_dwordx4 v[178:179], off
	s_add_i32 m0, vcc_hi, 0x2000
	v_lshl_add_u64 v[224:225], s[98:99], 0, v[146:147]
	s_add_u32 s98, s98, s18
	s_addc_u32 s99, s99, 0
	s_add_i32 vcc_lo, vcc_lo, s83
	global_load_lds_dwordx4 v[224:225], off
	v_lshl_add_u64 v[226:227], s[98:99], 0, v[142:143]
	s_mov_b32 m0, vcc_lo
	v_lshl_add_u64 v[228:229], s[98:99], 0, v[146:147]
	global_load_lds_dwordx4 v[226:227], off
	s_add_i32 m0, vcc_lo, 0x2000
	v_lshl_add_u64 v[230:231], s[38:39], 0, v[140:141]
	global_load_lds_dwordx4 v[228:229], off
	s_mov_b32 m0, s36
	v_lshl_add_u64 v[232:233], s[38:39], 0, v[144:145]
	global_load_lds_dwordx4 v[230:231], off
	s_mov_b32 m0, s10
	s_nop 0
	global_load_lds_dwordx4 v[232:233], off
	s_waitcnt vmcnt(8)
	s_waitcnt lgkmcnt(0)
	s_barrier
; #define PG8_STAGE(bufoff, gbase, voff) do { _Pragma("unroll") for (int _i = 0; _i < 2; ++_i) \
;         __builtin_amdgcn_global_load_lds((const unsigned*)((const char*)(gbase) + (voff)[_i]), (PG8_LAS unsigned*)(lds + (bufoff) + ldsw + _i * 8192), 16, 0, 0); } while (0)
; #define PG8_LDA(dst, b, h) do { _Pragma("unroll") for (int m = 0; m < 4; ++m) _Pragma("unroll") for (int k = 0; k < 2; ++k) dst[m][k] = *(const PG8_LAS bf16x8*)(lds + PG8_SA(b, h) + aoff + m * 2048 + k * 1024); } while (0)
; #define PG8_LDB(dst, b, h) do { _Pragma("unroll") for (int n = 0; n < 2; ++n) _Pragma("unroll") for (int k = 0; k < 2; ++k) dst[n][k] = *(const PG8_LAS bf16x8*)(lds + PG8_SB(b, h) + boff + n * 2048 + k * 1024); } while (0)
; #define PG8_MMA(ai, bj, At, Bt) do { __builtin_amdgcn_s_setprio(1); _Pragma("unroll") for (int m = 0; m < 4; ++m) _Pragma("unroll") for (int n = 0; n < 2; ++n) _Pragma("unroll") for (int k = 0; k < 2; ++k) \
;         acc[ai][bj][m][n] = __builtin_amdgcn_mfma_f32_16x16x32_bf16(Bt[n][k], At[m][k], acc[ai][bj][m][n], 0, 0, 0); __builtin_amdgcn_s_setprio(0); } while (0)
; #define PG8_WAIT_V(n) asm volatile("s_waitcnt vmcnt(" #n ")" ::: "memory")
; #define PG8_WAIT_L(n) asm volatile("s_waitcnt lgkmcnt(" #n ")" ::: "memory")
; #define PG8_BAR __builtin_amdgcn_s_barrier()
; #define PG8_SCHED __builtin_amdgcn_sched_barrier(0)
; template <class Epi, class Sched, bool ALIGN_EPI = false, bool SP2 = false>
; __device__ __forceinline__ void gemm_phase(PG8_LAS unsigned char* lds, const Gemm g, const Sched& S, const Epi& E, const int wid_) {
;     ...
;             PG8_WAIT_V(8); PG8_WAIT_L(0); PG8_BAR; PG8_MMA(1, 0, At, B0); PG8_MMA(1, 1, At, B1); PG8_BAR; PG8_SCHED;
;             PG8_LDB(B0, 1, 0); PG8_LDB(B1, 1, 1); PG8_SCHED; PG8_LDA(At, 1, 0); PG8_STAGE(PG8_SA(0, 1), a2 + hstepA, voffA);
;             PG8_WAIT_V(8); PG8_WAIT_L(0); PG8_BAR; PG8_MMA(0, 0, At, B0); PG8_MMA(0, 1, At, B1); PG8_BAR; PG8_SCHED;
	s_waitcnt lgkmcnt(0)
	v_mfma_f32_16x16x32_bf16 v[60:63], v[128:131], v[190:193], v[60:63]
	v_mfma_f32_16x16x32_bf16 v[56:59], v[136:139], v[190:193], v[56:59]
	v_mfma_f32_16x16x32_bf16 v[52:55], v[128:131], v[198:201], v[52:55]
	v_mfma_f32_16x16x32_bf16 v[48:51], v[136:139], v[198:201], v[48:51]
	v_mfma_f32_16x16x32_bf16 v[36:39], v[128:131], v[206:209], v[36:39]
	v_mfma_f32_16x16x32_bf16 v[32:35], v[136:139], v[206:209], v[32:35]
	v_mfma_f32_16x16x32_bf16 v[20:23], v[128:131], v[216:219], v[20:23]
	v_mfma_f32_16x16x32_bf16 v[16:19], v[136:139], v[216:219], v[16:19]
	v_mfma_f32_16x16x32_bf16 v[60:63], v[132:135], v[194:197], v[60:63]
	v_mfma_f32_16x16x32_bf16 v[56:59], v[164:167], v[194:197], v[56:59]
	v_mfma_f32_16x16x32_bf16 v[52:55], v[132:135], v[202:205], v[52:55]
	v_mfma_f32_16x16x32_bf16 v[48:51], v[164:167], v[202:205], v[48:51]
	v_mfma_f32_16x16x32_bf16 v[36:39], v[132:135], v[212:215], v[36:39]
	v_mfma_f32_16x16x32_bf16 v[32:35], v[164:167], v[212:215], v[32:35]
	v_mfma_f32_16x16x32_bf16 v[20:23], v[132:135], v[220:223], v[20:23]
	v_mfma_f32_16x16x32_bf16 v[16:19], v[164:167], v[220:223], v[16:19]
	v_mfma_f32_16x16x32_bf16 v[44:47], v[168:171], v[190:193], v[44:47]
	v_mfma_f32_16x16x32_bf16 v[40:43], v[182:185], v[190:193], v[40:43]
	v_mfma_f32_16x16x32_bf16 v[28:31], v[168:171], v[198:201], v[28:31]
	v_mfma_f32_16x16x32_bf16 v[24:27], v[182:185], v[198:201], v[24:27]
	v_mfma_f32_16x16x32_bf16 v[12:15], v[168:171], v[206:209], v[12:15]
	v_mfma_f32_16x16x32_bf16 v[8:11], v[182:185], v[206:209], v[8:11]
	v_mfma_f32_16x16x32_bf16 v[4:7], v[168:171], v[216:219], v[4:7]
	v_mfma_f32_16x16x32_bf16 v[0:3], v[182:185], v[216:219], v[0:3]
	v_mfma_f32_16x16x32_bf16 v[44:47], v[172:175], v[194:197], v[44:47]
	v_mfma_f32_16x16x32_bf16 v[40:43], v[186:189], v[194:197], v[40:43]
	v_mfma_f32_16x16x32_bf16 v[28:31], v[172:175], v[202:205], v[28:31]
	v_mfma_f32_16x16x32_bf16 v[24:27], v[186:189], v[202:205], v[24:27]
	v_mfma_f32_16x16x32_bf16 v[12:15], v[172:175], v[212:215], v[12:15]
	v_mfma_f32_16x16x32_bf16 v[8:11], v[186:189], v[212:215], v[8:11]
	v_mfma_f32_16x16x32_bf16 v[4:7], v[172:175], v[220:223], v[4:7]
	v_mfma_f32_16x16x32_bf16 v[0:3], v[186:189], v[220:223], v[0:3]
	s_barrier
	s_add_i32 s98, 0, 0x18000
	s_add_i32 s99, 0, 0x1c000
	v_add_u32_e32 v164, s98, v180
	v_add_u32_e32 v176, s99, v180
	ds_read_b128 v[128:131], v164
	ds_read_b128 v[132:135], v164 offset:1024
	ds_read_b128 v[136:139], v164 offset:2048
	ds_read_b128 v[164:167], v164 offset:3072
	ds_read_b128 v[168:171], v176
	ds_read_b128 v[172:175], v176 offset:1024
	ds_read_b128 v[182:185], v176 offset:2048
	ds_read_b128 v[186:189], v176 offset:3072
	s_add_u32 s38, s38, s88
	s_addc_u32 s39, s39, 0
	s_mov_b32 m0, s11
	v_lshl_add_u64 v[234:235], s[38:39], 0, v[140:141]
	ds_read_b128 v[190:193], v181 offset:32768
	ds_read_b128 v[194:197], v181 offset:33792
	ds_read_b128 v[198:201], v181 offset:34816
	ds_read_b128 v[202:205], v181 offset:35840
	ds_read_b128 v[206:209], v181 offset:36864
	ds_read_b128 v[212:215], v181 offset:37888
	ds_read_b128 v[216:219], v181 offset:38912
	ds_read_b128 v[220:223], v181 offset:39936
	global_load_lds_dwordx4 v[234:235], off
	v_lshl_add_u64 v[234:235], s[38:39], 0, v[144:145]
	s_mov_b32 m0, s55
	s_nop 0
	global_load_lds_dwordx4 v[234:235], off
	s_waitcnt vmcnt(8)
	s_waitcnt lgkmcnt(0)
	s_barrier
	s_waitcnt lgkmcnt(0)
	v_mfma_f32_16x16x32_bf16 v[124:127], v[128:131], v[190:193], v[124:127]
	v_mfma_f32_16x16x32_bf16 v[120:123], v[136:139], v[190:193], v[120:123]
	v_mfma_f32_16x16x32_bf16 v[116:119], v[128:131], v[198:201], v[116:119]
	v_mfma_f32_16x16x32_bf16 v[112:115], v[136:139], v[198:201], v[112:115]
	v_mfma_f32_16x16x32_bf16 v[100:103], v[128:131], v[206:209], v[100:103]
	v_mfma_f32_16x16x32_bf16 v[96:99], v[136:139], v[206:209], v[96:99]
	v_mfma_f32_16x16x32_bf16 v[84:87], v[128:131], v[216:219], v[84:87]
	v_mfma_f32_16x16x32_bf16 v[80:83], v[136:139], v[216:219], v[80:83]
	v_mfma_f32_16x16x32_bf16 v[124:127], v[132:135], v[194:197], v[124:127]
	v_mfma_f32_16x16x32_bf16 v[120:123], v[164:167], v[194:197], v[120:123]
	v_mfma_f32_16x16x32_bf16 v[116:119], v[132:135], v[202:205], v[116:119]
	v_mfma_f32_16x16x32_bf16 v[112:115], v[164:167], v[202:205], v[112:115]
	v_mfma_f32_16x16x32_bf16 v[100:103], v[132:135], v[212:215], v[100:103]
	v_mfma_f32_16x16x32_bf16 v[96:99], v[164:167], v[212:215], v[96:99]
	v_mfma_f32_16x16x32_bf16 v[84:87], v[132:135], v[220:223], v[84:87]
	v_mfma_f32_16x16x32_bf16 v[80:83], v[164:167], v[220:223], v[80:83]
	v_mfma_f32_16x16x32_bf16 v[108:111], v[168:171], v[190:193], v[108:111]
	v_mfma_f32_16x16x32_bf16 v[104:107], v[182:185], v[190:193], v[104:107]
	v_mfma_f32_16x16x32_bf16 v[92:95], v[168:171], v[198:201], v[92:95]
	v_mfma_f32_16x16x32_bf16 v[88:91], v[182:185], v[198:201], v[88:91]
	v_mfma_f32_16x16x32_bf16 v[76:79], v[168:171], v[206:209], v[76:79]
	v_mfma_f32_16x16x32_bf16 v[72:75], v[182:185], v[206:209], v[72:75]
	v_mfma_f32_16x16x32_bf16 v[68:71], v[168:171], v[216:219], v[68:71]
	v_mfma_f32_16x16x32_bf16 v[64:67], v[182:185], v[216:219], v[64:67]
	v_mfma_f32_16x16x32_bf16 v[108:111], v[172:175], v[194:197], v[108:111]
	v_mfma_f32_16x16x32_bf16 v[104:107], v[186:189], v[194:197], v[104:107]
	v_mfma_f32_16x16x32_bf16 v[92:95], v[172:175], v[202:205], v[92:95]
	v_mfma_f32_16x16x32_bf16 v[88:91], v[186:189], v[202:205], v[88:91]
	v_mfma_f32_16x16x32_bf16 v[76:79], v[172:175], v[212:215], v[76:79]
	v_mfma_f32_16x16x32_bf16 v[72:75], v[186:189], v[212:215], v[72:75]
	v_mfma_f32_16x16x32_bf16 v[68:71], v[172:175], v[220:223], v[68:71]
	v_mfma_f32_16x16x32_bf16 v[64:67], v[186:189], v[220:223], v[64:67]
	s_barrier
; #define PG8_STAGE(bufoff, gbase, voff) do { _Pragma("unroll") for (int _i = 0; _i < 2; ++_i) \
;         __builtin_amdgcn_global_load_lds((const unsigned*)((const char*)(gbase) + (voff)[_i]), (PG8_LAS unsigned*)(lds + (bufoff) + ldsw + _i * 8192), 16, 0, 0); } while (0)
; #define PG8_LDA(dst, b, h) do { _Pragma("unroll") for (int m = 0; m < 4; ++m) _Pragma("unroll") for (int k = 0; k < 2; ++k) dst[m][k] = *(const PG8_LAS bf16x8*)(lds + PG8_SA(b, h) + aoff + m * 2048 + k * 1024); } while (0)
; #define PG8_MMA(ai, bj, At, Bt) do { __builtin_amdgcn_s_setprio(1); _Pragma("unroll") for (int m = 0; m < 4; ++m) _Pragma("unroll") for (int n = 0; n < 2; ++n) _Pragma("unroll") for (int k = 0; k < 2; ++k) \
;         acc[ai][bj][m][n] = __builtin_amdgcn_mfma_f32_16x16x32_bf16(Bt[n][k], At[m][k], acc[ai][bj][m][n], 0, 0, 0); __builtin_amdgcn_s_setprio(0); } while (0)
; #define PG8_WAIT_V(n) asm volatile("s_waitcnt vmcnt(" #n ")" ::: "memory")
; #define PG8_WAIT_L(n) asm volatile("s_waitcnt lgkmcnt(" #n ")" ::: "memory")
; #define PG8_BAR __builtin_amdgcn_s_barrier()
; #define PG8_SCHED __builtin_amdgcn_sched_barrier(0)
; template <class Epi, class Sched, bool ALIGN_EPI = false, bool SP2 = false>
; __device__ __forceinline__ void gemm_phase(PG8_LAS unsigned char* lds, const Gemm g, const Sched& S, const Epi& E, const int wid_) {
;     ...
;             PG8_LDA(At, 1, 1); PG8_STAGE(PG8_SB(1, 0), b3, voffB); PG8_STAGE(PG8_SB(1, 1), b3 + hstepB, voffB); PG8_STAGE(PG8_SA(1, 0), a3, voffA);
;             PG8_WAIT_V(8); PG8_WAIT_L(0); PG8_BAR; PG8_MMA(1, 0, At, B0); PG8_MMA(1, 1, At, B1); PG8_BAR; PG8_SCHED;
;     ...
;         if constexpr (ALIGN_EPI) { if (wr == 0) PG8_BAR; }
	s_add_i32 s38, s98, s83
	v_lshl_add_u64 v[178:179], v[178:179], 0, s[66:67]
	s_mov_b32 m0, s38
	ds_read_b128 v[190:193], v181 offset:49152
	ds_read_b128 v[194:197], v181 offset:50176
	ds_read_b128 v[198:201], v181 offset:51200
	ds_read_b128 v[202:205], v181 offset:52224
	ds_read_b128 v[206:209], v181 offset:53248
	ds_read_b128 v[212:215], v181 offset:54272
	ds_read_b128 v[216:219], v181 offset:55296
	ds_read_b128 v[220:223], v181 offset:56320
	global_load_lds_dwordx4 v[178:179], off
	v_lshl_add_u64 v[178:179], v[224:225], 0, s[66:67]
	s_add_i32 m0, s38, 0x2000
	s_add_i32 s38, s99, s83
	global_load_lds_dwordx4 v[178:179], off
	v_lshl_add_u64 v[178:179], v[226:227], 0, s[66:67]
	s_mov_b32 m0, s38
	s_nop 0
	global_load_lds_dwordx4 v[178:179], off
	v_lshl_add_u64 v[178:179], v[228:229], 0, s[66:67]
	s_add_i32 m0, s38, 0x2000
	s_nop 0
	global_load_lds_dwordx4 v[178:179], off
	v_lshl_add_u64 v[178:179], v[230:231], 0, s[66:67]
	s_mov_b32 m0, s33
	s_nop 0
	global_load_lds_dwordx4 v[178:179], off
	v_lshl_add_u64 v[178:179], v[232:233], 0, s[66:67]
	s_mov_b32 m0, s52
	s_nop 0
	global_load_lds_dwordx4 v[178:179], off
	s_waitcnt vmcnt(8)
	s_waitcnt lgkmcnt(0)
	s_barrier
	s_waitcnt lgkmcnt(0)
	v_mfma_f32_16x16x32_bf16 v[60:63], v[128:131], v[190:193], v[60:63]
	v_mfma_f32_16x16x32_bf16 v[56:59], v[136:139], v[190:193], v[56:59]
	v_mfma_f32_16x16x32_bf16 v[52:55], v[128:131], v[198:201], v[52:55]
	v_mfma_f32_16x16x32_bf16 v[48:51], v[136:139], v[198:201], v[48:51]
	v_mfma_f32_16x16x32_bf16 v[36:39], v[128:131], v[206:209], v[36:39]
	v_mfma_f32_16x16x32_bf16 v[32:35], v[136:139], v[206:209], v[32:35]
	v_mfma_f32_16x16x32_bf16 v[20:23], v[128:131], v[216:219], v[20:23]
	v_mfma_f32_16x16x32_bf16 v[16:19], v[136:139], v[216:219], v[16:19]
	v_mfma_f32_16x16x32_bf16 v[60:63], v[132:135], v[194:197], v[60:63]
	v_mfma_f32_16x16x32_bf16 v[56:59], v[164:167], v[194:197], v[56:59]
	v_mfma_f32_16x16x32_bf16 v[52:55], v[132:135], v[202:205], v[52:55]
	v_mfma_f32_16x16x32_bf16 v[48:51], v[164:167], v[202:205], v[48:51]
	v_mfma_f32_16x16x32_bf16 v[36:39], v[132:135], v[212:215], v[36:39]
	v_mfma_f32_16x16x32_bf16 v[32:35], v[164:167], v[212:215], v[32:35]
	v_mfma_f32_16x16x32_bf16 v[20:23], v[132:135], v[220:223], v[20:23]
	v_mfma_f32_16x16x32_bf16 v[16:19], v[164:167], v[220:223], v[16:19]
	v_mfma_f32_16x16x32_bf16 v[44:47], v[168:171], v[190:193], v[44:47]
	v_mfma_f32_16x16x32_bf16 v[40:43], v[182:185], v[190:193], v[40:43]
	v_mfma_f32_16x16x32_bf16 v[28:31], v[168:171], v[198:201], v[28:31]
	v_mfma_f32_16x16x32_bf16 v[24:27], v[182:185], v[198:201], v[24:27]
	v_mfma_f32_16x16x32_bf16 v[12:15], v[168:171], v[206:209], v[12:15]
	v_mfma_f32_16x16x32_bf16 v[8:11], v[182:185], v[206:209], v[8:11]
	v_mfma_f32_16x16x32_bf16 v[4:7], v[168:171], v[216:219], v[4:7]
	v_mfma_f32_16x16x32_bf16 v[0:3], v[182:185], v[216:219], v[0:3]
	v_mfma_f32_16x16x32_bf16 v[44:47], v[172:175], v[194:197], v[44:47]
	v_mfma_f32_16x16x32_bf16 v[40:43], v[186:189], v[194:197], v[40:43]
	v_mfma_f32_16x16x32_bf16 v[28:31], v[172:175], v[202:205], v[28:31]
	v_mfma_f32_16x16x32_bf16 v[24:27], v[186:189], v[202:205], v[24:27]
	v_mfma_f32_16x16x32_bf16 v[12:15], v[172:175], v[212:215], v[12:15]
	v_mfma_f32_16x16x32_bf16 v[8:11], v[186:189], v[212:215], v[8:11]
	v_mfma_f32_16x16x32_bf16 v[4:7], v[172:175], v[220:223], v[4:7]
	v_mfma_f32_16x16x32_bf16 v[0:3], v[186:189], v[220:223], v[0:3]
	s_barrier
	s_add_u32 s49, s49, 0x100
	s_addc_u32 s62, s62, 0
	s_add_u32 s6, s6, 0x100
	s_addc_u32 s7, s7, 0
	s_cmp_ge_u32 s97, s71
	s_mov_b32 s38, s97
	s_cbranch_scc0 .LBB0_380
	s_setprio 0
	s_and_b64 vcc, s[94:95], s[4:5]
	s_cbranch_vccz .LBB0_384
	s_barrier
	v_lshl_add_u32 v164, s48, 8, v153
	s_cmp_lt_i32 s37, 2
	s_mov_b64 s[6:7], -1
	s_cbranch_scc0 .LBB0_385

; #define PG8_BAR __builtin_amdgcn_s_barrier()
; template <class Epi, class Sched, bool ALIGN_EPI = false, bool SP2 = false>
; __device__ __forceinline__ void gemm_phase(PG8_LAS unsigned char* lds, const Gemm g, const Sched& S, const Epi& E, const int wid_) {
;     ...
;         if constexpr (ALIGN_EPI) { if (wr == 0) PG8_BAR; }
;         if constexpr (!Epi::AFTER_DRAIN) { E(acc, cur, wr, wc, fr, fq); S.done(cur); }
;         if (!has_next) break;
; #pragma unroll
;         for (int a = 0; a < 2; ++a)
; #pragma unroll
;             for (int b = 0; b < 2; ++b)
; #pragma unroll
;                 for (int m = 0; m < 4; ++m)
; #pragma unroll
;                     for (int n = 0; n < 2; ++n) acc[a][b][m][n] = (f32x4){0.f, 0.f, 0.f, 0.f};
;         cur = nxt; cA = nA; cB = nB; ++ui;
;         if constexpr (ALIGN_EPI) { if (wr == 1) PG8_BAR; }
;     }
.LBB0_592:
	s_and_b64 vcc, exec, s[4:5]
	s_mov_b64 s[4:5], -1
	s_cbranch_vccnz .LBB0_368
	s_andn2_b64 vcc, exec, s[92:93]
	s_cbranch_vccnz .LBB0_367
	s_branch .LBB0_367
